# rsqrt cache also used by the conv pair GEMM epilogue mode
# speedup vs baseline: 1.0118x; 1.0060x over previous
.LBB0_143:
	s_mov_b32 s53, s34
	v_readlane_b32 s40, v249, 54
	v_readlane_b32 s41, v249, 55
	v_readlane_b32 s52, v248, 41
	s_cmp_eq_u32 s52, s34
	s_cbranch_scc1 .Lepc_hit
